# attention DMA issue block placed per wave half: priority waves 4-7 issue behind their last QK MFMA, waves 0-3 at the tile top
# speedup vs baseline: 1.0058x; 1.0035x over previous
.LBB0_106:
	v_mov_b32_e32 v14, v0
	v_mov_b32_e32 v15, v0
	s_waitcnt vmcnt(0) lgkmcnt(0)
	s_barrier
	v_mov_b32_e32 v1, v0
	v_mov_b32_e32 v2, v0
	v_mov_b32_e32 v3, v0
	v_mov_b32_e32 v4, v0
	v_mov_b32_e32 v5, v0
	v_mov_b32_e32 v6, v0
	v_mov_b32_e32 v7, v0
	v_mov_b32_e32 v8, v0
	v_mov_b32_e32 v9, v0
	v_mov_b32_e32 v10, v0
	v_mov_b32_e32 v11, v0
	v_mov_b32_e32 v12, v0
	v_mov_b32_e32 v13, v0
	s_lshl_b32 s30, s43, 12
	s_lshl_b32 s44, s48, 7
	v_mov_b64_e32 v[62:63], v[14:15]
	v_mov_b64_e32 v[46:47], v[14:15]
	v_mov_b64_e32 v[30:31], v[14:15]
	s_add_i32 s43, s30, 0xffffff80
	v_add_u32_e32 v153, s44, v171
	v_add_u32_e32 v155, s44, v172
	s_add_i32 s45, s46, 0x80
	s_mov_b32 s50, 2
	s_mov_b32 s51, 1
	s_mov_b32 s53, 0
	v_mov_b32_e32 v157, 0
	v_mov_b32_e32 v159, 0
	v_mov_b32_e32 v96, 0
	v_mov_b32_e32 v97, 0
	v_mov_b32_e32 v98, 0
	v_mov_b32_e32 v99, 0
	v_mov_b32_e32 v100, 0
	v_mov_b32_e32 v101, 0
	v_mov_b32_e32 v102, 0
	v_mov_b32_e32 v103, 0
	v_mov_b32_e32 v104, 0
	v_mov_b32_e32 v105, 0
	v_mov_b32_e32 v106, 0
	v_mov_b32_e32 v107, 0
	v_mov_b32_e32 v108, 0
	v_mov_b32_e32 v109, 0
	v_mov_b32_e32 v110, 0
	v_mov_b32_e32 v111, 0
	v_mov_b64_e32 v[60:61], v[12:13]
	v_mov_b64_e32 v[58:59], v[10:11]
	v_mov_b64_e32 v[56:57], v[8:9]
	v_mov_b64_e32 v[54:55], v[6:7]
	v_mov_b64_e32 v[52:53], v[4:5]
	v_mov_b64_e32 v[50:51], v[2:3]
	v_mov_b64_e32 v[48:49], v[0:1]
	v_mov_b64_e32 v[44:45], v[12:13]
	v_mov_b64_e32 v[42:43], v[10:11]
	v_mov_b64_e32 v[40:41], v[8:9]
	v_mov_b64_e32 v[38:39], v[6:7]
	v_mov_b64_e32 v[36:37], v[4:5]
	v_mov_b64_e32 v[34:35], v[2:3]
	v_mov_b64_e32 v[32:33], v[0:1]
	v_mov_b64_e32 v[28:29], v[12:13]
	v_mov_b64_e32 v[26:27], v[10:11]
	v_mov_b64_e32 v[24:25], v[8:9]
	v_mov_b64_e32 v[22:23], v[6:7]
	v_mov_b64_e32 v[20:21], v[4:5]
	v_mov_b64_e32 v[18:19], v[2:3]
	v_mov_b64_e32 v[16:17], v[0:1]
	s_mov_b32 s52, 0
	s_waitcnt vmcnt(0)
	s_mul_i32 s30, s53, 0x2400
	v_add_u32_e32 v242, s30, v173
	s_mul_i32 s30, s53, 0x4800
	v_add_u32_e32 v243, s30, v174
	v_readfirstlane_b32 s99, v191
	s_lshr_b32 s99, s99, 8
	v_readfirstlane_b32 s30, v191
	s_lshr_b32 s30, s30, 8
	s_cmp_eq_u32 s30, 0
	s_cbranch_scc1 .Latt_diff_p0
	s_setprio 1
.Latt_diff_p0:
.LBB0_107:
.LBB0_116:
	ds_read_b128 v[112:115], v242 offset:0
	ds_read_b128 v[116:119], v242 offset:32
	ds_read_b128 v[120:123], v242 offset:64
	ds_read_b128 v[124:127], v242 offset:96
	s_cmp_lg_u32 s99, 0
	s_cbranch_scc1 .Latt_diff_dmaendA
	s_add_i32 s30, s52, 2
	s_cmp_ge_u32 s30, s21
	s_cselect_b64 s[46:47], -1, 0
	s_cbranch_scc1 .Latt_diff_dmaendA
	s_cmp_lt_u32 s52, 2
	s_cselect_b32 s48, s45, s43
	s_mul_i32 s55, s50, 0x2400
	s_add_i32 s56, s55, s41
	s_mov_b32 m0, s56
	v_lshl_add_u32 v244, s48, 12, v153
	global_load_lds_dwordx4 v244, s[18:19]
	s_ashr_i32 s49, s48, 31
	s_lshl_b64 s[30:31], s[48:49], 1
	s_add_i32 s55, s55, s56
	s_add_i32 m0, s55, 0x6c00
	s_add_u32 s30, s39, s30
	s_addc_u32 s31, s42, s31
	global_load_lds_dwordx4 v150, s[30:31]
	s_add_i32 m0, s55, 0x8c00
	s_and_b64 vcc, exec, s[14:15]
	global_load_lds_dwordx4 v148, s[30:31]
	s_cbranch_vccz .Latt_diff_dmaxA
.Latt_diff_dmaendA:
	s_waitcnt lgkmcnt(2)
	v_mfma_f32_32x32x16_bf16 v[64:79], v[112:115], v[130:133], v[96:111]
	ds_read_b128 v[112:115], v242 offset:4608
	v_mfma_f32_32x32x16_bf16 v[64:79], v[116:119], v[134:137], v[64:79]
	ds_read_b128 v[116:119], v242 offset:4640
	s_waitcnt lgkmcnt(2)
	v_mfma_f32_32x32x16_bf16 v[64:79], v[120:123], v[138:141], v[64:79]
	ds_read_b128 v[120:123], v242 offset:4672
	v_mfma_f32_32x32x16_bf16 v[64:79], v[124:127], v[142:145], v[64:79]
	ds_read_b128 v[124:127], v242 offset:4704
	s_waitcnt lgkmcnt(2)
	v_mfma_f32_32x32x16_bf16 v[80:95], v[112:115], v[130:133], v[96:111]
	v_mfma_f32_32x32x16_bf16 v[80:95], v[116:119], v[134:137], v[80:95]
	s_waitcnt lgkmcnt(0)
	v_mfma_f32_32x32x16_bf16 v[80:95], v[120:123], v[138:141], v[80:95]
	v_mfma_f32_32x32x16_bf16 v[80:95], v[124:127], v[142:145], v[80:95]
	ds_read_b128 v[112:115], v243 offset:27648
	ds_read_b128 v[116:119], v243 offset:32256
	ds_read_b128 v[120:123], v243 offset:36864
	ds_read_b128 v[124:127], v243 offset:41472
	s_cmp_eq_u32 s99, 0
	s_cbranch_scc1 .Latt_diff_dmaendB
	s_add_i32 s30, s52, 2
	s_cmp_ge_u32 s30, s21
	s_cselect_b64 s[46:47], -1, 0
	s_cbranch_scc1 .Latt_diff_dmaendB
	s_cmp_lt_u32 s52, 2
	s_cselect_b32 s48, s45, s43
	s_mul_i32 s55, s50, 0x2400
	s_add_i32 s56, s55, s41
	s_mov_b32 m0, s56
	v_lshl_add_u32 v244, s48, 12, v153
	global_load_lds_dwordx4 v244, s[18:19]
	s_ashr_i32 s49, s48, 31
	s_lshl_b64 s[30:31], s[48:49], 1
	s_add_i32 s55, s55, s56
	s_add_i32 m0, s55, 0x6c00
	s_add_u32 s30, s39, s30
	s_addc_u32 s31, s42, s31
	global_load_lds_dwordx4 v150, s[30:31]
	s_add_i32 m0, s55, 0x8c00
	s_and_b64 vcc, exec, s[14:15]
	global_load_lds_dwordx4 v148, s[30:31]
	s_cbranch_vccz .Latt_diff_dmaxB
.Latt_diff_dmaendB:
	s_cmp_eq_u32 s52, 0
	s_cselect_b32 s31, 0xff7fffff, 0
	v_max3_f32 v227, v64, v65, v66
	v_max3_f32 v228, v67, v68, v69
	v_max3_f32 v227, v227, v70, v71
	v_max3_f32 v228, v228, v72, v73
	v_max3_f32 v227, v227, v74, v75
	v_max3_f32 v228, v228, v76, v77
	v_max3_f32 v227, v227, v78, v79
	v_max3_f32 v229, v80, v81, v82
	v_max3_f32 v226, v83, v84, v85
	v_max3_f32 v229, v229, v86, v87
	v_max3_f32 v226, v226, v88, v89
	v_max3_f32 v229, v229, v90, v91
	v_max3_f32 v226, v226, v92, v93
	v_max3_f32 v229, v229, v94, v95
	v_max3_f32 v226, v226, v227, v228
	v_max_f32_e32 v226, v226, v229
	v_cmp_lt_f32_e32 vcc, s58, v226
	s_cmp_eq_u32 s52, 0
	s_cbranch_scc1 .Latt_diff_rare
	s_cbranch_vccnz .Latt_diff_rare

.LBB0_177:
	v_mov_b32_e32 v14, v0
	v_mov_b32_e32 v15, v0
	s_waitcnt vmcnt(0) lgkmcnt(0)
	s_barrier
	v_mov_b32_e32 v1, v0
	v_mov_b32_e32 v2, v0
	v_mov_b32_e32 v3, v0
	v_mov_b32_e32 v4, v0
	v_mov_b32_e32 v5, v0
	v_mov_b32_e32 v6, v0
	v_mov_b32_e32 v7, v0
	v_mov_b32_e32 v8, v0
	v_mov_b32_e32 v9, v0
	v_mov_b32_e32 v10, v0
	v_mov_b32_e32 v11, v0
	v_mov_b32_e32 v12, v0
	v_mov_b32_e32 v13, v0
	s_lshl_b32 s49, s49, 12
	v_mov_b64_e32 v[30:31], v[14:15]
	v_mov_b64_e32 v[46:47], v[14:15]
	v_mov_b64_e32 v[62:63], v[14:15]
	v_mad_u64_u32 v[222:223], s[30:31], s50, v238, v[190:191]
	v_mad_u64_u32 v[224:225], s[30:31], s50, v240, v[192:193]
	v_mad_u64_u32 v[226:227], s[30:31], s50, v242, v[194:195]
	v_mad_u64_u32 v[228:229], s[30:31], s50, v244, v[196:197]
	s_addk_i32 s49, 0xff80
	s_add_i32 s51, s60, 0x80
	s_mov_b32 s52, 2
	s_mov_b32 s53, 1
	s_mov_b32 s56, 0
	v_mov_b32_e32 v205, 0
	v_mov_b32_e32 v207, 0
	v_mov_b32_e32 v96, 0
	v_mov_b32_e32 v97, 0
	v_mov_b32_e32 v98, 0
	v_mov_b32_e32 v99, 0
	v_mov_b32_e32 v100, 0
	v_mov_b32_e32 v101, 0
	v_mov_b32_e32 v102, 0
	v_mov_b32_e32 v103, 0
	v_mov_b32_e32 v104, 0
	v_mov_b32_e32 v105, 0
	v_mov_b32_e32 v106, 0
	v_mov_b32_e32 v107, 0
	v_mov_b32_e32 v108, 0
	v_mov_b32_e32 v109, 0
	v_mov_b32_e32 v110, 0
	v_mov_b32_e32 v111, 0
	v_mov_b64_e32 v[28:29], v[12:13]
	v_mov_b64_e32 v[26:27], v[10:11]
	v_mov_b64_e32 v[24:25], v[8:9]
	v_mov_b64_e32 v[22:23], v[6:7]
	v_mov_b64_e32 v[20:21], v[4:5]
	v_mov_b64_e32 v[18:19], v[2:3]
	v_mov_b64_e32 v[16:17], v[0:1]
	v_mov_b64_e32 v[44:45], v[12:13]
	v_mov_b64_e32 v[42:43], v[10:11]
	v_mov_b64_e32 v[40:41], v[8:9]
	v_mov_b64_e32 v[38:39], v[6:7]
	v_mov_b64_e32 v[36:37], v[4:5]
	v_mov_b64_e32 v[34:35], v[2:3]
	v_mov_b64_e32 v[32:33], v[0:1]
	v_mov_b64_e32 v[60:61], v[12:13]
	v_mov_b64_e32 v[58:59], v[10:11]
	v_mov_b64_e32 v[56:57], v[8:9]
	v_mov_b64_e32 v[54:55], v[6:7]
	v_mov_b64_e32 v[52:53], v[4:5]
	v_mov_b64_e32 v[50:51], v[2:3]
	v_mov_b64_e32 v[48:49], v[0:1]
	s_mov_b32 s55, 0
	s_waitcnt vmcnt(0)
	s_mul_i32 s30, s56, 0x6400
	v_add_u32_e32 v209, s30, v246
	s_mul_i32 s30, s56, 0x4800
	v_add_u32_e32 v219, s30, v247
	v_readfirstlane_b32 s99, v191
	s_lshr_b32 s99, s99, 8
	v_readfirstlane_b32 s30, v191
	s_lshr_b32 s30, s30, 8
	s_cmp_eq_u32 s30, 0
	s_cbranch_scc1 .Latt_mla_p0
	s_setprio 1
.Latt_mla_p0:
.LBB0_178:
.LBB0_191:
	ds_read_b128 v[112:115], v209 offset:0
	ds_read_b128 v[116:119], v209 offset:32
	ds_read_b128 v[120:123], v209 offset:64
	ds_read_b128 v[124:127], v209 offset:96
	ds_read_b128 v[250:253], v209 offset:128
	s_cmp_lg_u32 s99, 0
	s_cbranch_scc1 .Latt_mla_dmaendA
	s_add_i32 s30, s55, 2
	s_cmp_ge_u32 s30, s20
	s_cselect_b64 s[60:61], -1, 0
	s_cbranch_scc1 .Latt_mla_dmaendA
	s_cmp_lt_u32 s55, 2
	s_cselect_b32 s62, s51, s49
	s_mul_i32 s57, s52, 0x6400
	s_add_i32 s57, s57, s42
	s_mov_b32 m0, s57
	v_mad_u32_u24 v217, s62, v237, v222
	global_load_lds_dwordx4 v217, s[2:3]
	s_add_i32 m0, s57, 0x2000
	v_mad_u32_u24 v217, s62, v239, v224
	global_load_lds_dwordx4 v217, s[2:3]
	s_add_i32 m0, s57, 0x4000
	v_mad_u32_u24 v217, s62, v241, v226
	global_load_lds_dwordx4 v217, s[2:3]
	s_ashr_i32 s63, s62, 31
	s_lshl_b64 s[30:31], s[62:63], 1
	s_mul_i32 s63, s52, 0x4800
	s_add_i32 s63, s63, s42
	s_add_i32 m0, s63, 0x12c00
	s_add_u32 s30, s21, s30
	s_addc_u32 s31, s43, s31
	global_load_lds_dwordx4 v202, s[30:31]
	s_add_i32 m0, s63, 0x14c00
	s_and_b64 vcc, exec, s[18:19]
	global_load_lds_dwordx4 v200, s[30:31]
	s_cbranch_vccz .Latt_mla_dmaxA
.Latt_mla_dmaendA:
	s_waitcnt lgkmcnt(3)
	v_mfma_f32_32x32x16_bf16 v[64:79], v[112:115], v[130:133], v[96:111]
	ds_read_b128 v[112:115], v209 offset:160
	v_mfma_f32_32x32x16_bf16 v[64:79], v[116:119], v[134:137], v[64:79]
	ds_read_b128 v[116:119], v209 offset:192
	s_waitcnt lgkmcnt(3)
	v_mfma_f32_32x32x16_bf16 v[64:79], v[120:123], v[138:141], v[64:79]
	ds_read_b128 v[120:123], v209 offset:224
	v_mfma_f32_32x32x16_bf16 v[64:79], v[124:127], v[142:145], v[64:79]
	ds_read_b128 v[124:127], v209 offset:256
	s_waitcnt lgkmcnt(3)
	v_mfma_f32_32x32x16_bf16 v[64:79], v[250:253], v[146:149], v[64:79]
	ds_read_b128 v[250:253], v209 offset:288
	v_mfma_f32_32x32x16_bf16 v[64:79], v[112:115], v[150:153], v[64:79]
	ds_read_b128 v[112:115], v209 offset:320
	s_waitcnt lgkmcnt(3)
	v_mfma_f32_32x32x16_bf16 v[64:79], v[116:119], v[154:157], v[64:79]
	ds_read_b128 v[116:119], v209 offset:352
	v_mfma_f32_32x32x16_bf16 v[64:79], v[120:123], v[158:161], v[64:79]
	ds_read_b128 v[120:123], v209 offset:12800
	s_waitcnt lgkmcnt(3)
	v_mfma_f32_32x32x16_bf16 v[64:79], v[124:127], v[162:165], v[64:79]
	ds_read_b128 v[124:127], v209 offset:12832
	v_mfma_f32_32x32x16_bf16 v[64:79], v[250:253], v[166:169], v[64:79]
	ds_read_b128 v[250:253], v209 offset:12864
	s_waitcnt lgkmcnt(3)
	v_mfma_f32_32x32x16_bf16 v[64:79], v[112:115], v[170:173], v[64:79]
	ds_read_b128 v[112:115], v209 offset:12896
	v_mfma_f32_32x32x16_bf16 v[64:79], v[116:119], v[174:177], v[64:79]
	ds_read_b128 v[116:119], v209 offset:12928
	s_waitcnt lgkmcnt(3)
	v_mfma_f32_32x32x16_bf16 v[80:95], v[120:123], v[130:133], v[96:111]
	ds_read_b128 v[120:123], v209 offset:12960
	v_mfma_f32_32x32x16_bf16 v[80:95], v[124:127], v[134:137], v[80:95]
	ds_read_b128 v[124:127], v209 offset:12992
	s_waitcnt lgkmcnt(3)
	v_mfma_f32_32x32x16_bf16 v[80:95], v[250:253], v[138:141], v[80:95]
	ds_read_b128 v[250:253], v209 offset:13024
	v_mfma_f32_32x32x16_bf16 v[80:95], v[112:115], v[142:145], v[80:95]
	ds_read_b128 v[112:115], v209 offset:13056
	s_waitcnt lgkmcnt(3)
	v_mfma_f32_32x32x16_bf16 v[80:95], v[116:119], v[146:149], v[80:95]
	ds_read_b128 v[116:119], v209 offset:13088
	v_max3_f32 v211, v64, v65, v66
	v_mfma_f32_32x32x16_bf16 v[80:95], v[120:123], v[150:153], v[80:95]
	ds_read_b128 v[120:123], v209 offset:13120
	v_max3_f32 v213, v67, v68, v69
	s_waitcnt lgkmcnt(3)
	v_mfma_f32_32x32x16_bf16 v[80:95], v[124:127], v[154:157], v[80:95]
	ds_read_b128 v[124:127], v209 offset:13152
	v_max3_f32 v211, v211, v70, v71
	v_mfma_f32_32x32x16_bf16 v[80:95], v[250:253], v[158:161], v[80:95]
	v_max3_f32 v213, v213, v72, v73
	s_waitcnt lgkmcnt(2)
	v_mfma_f32_32x32x16_bf16 v[80:95], v[112:115], v[162:165], v[80:95]
	v_max3_f32 v211, v211, v74, v75
	v_mfma_f32_32x32x16_bf16 v[80:95], v[116:119], v[166:169], v[80:95]
	v_max3_f32 v213, v213, v76, v77
	s_waitcnt lgkmcnt(0)
	v_mfma_f32_32x32x16_bf16 v[80:95], v[120:123], v[170:173], v[80:95]
	v_max3_f32 v211, v211, v78, v79
	v_mfma_f32_32x32x16_bf16 v[80:95], v[124:127], v[174:177], v[80:95]
	ds_read_b128 v[112:115], v219 offset:0
	ds_read_b128 v[116:119], v219 offset:4608
	ds_read_b128 v[120:123], v219 offset:9216
	s_cmp_eq_u32 s99, 0
	s_cbranch_scc1 .Latt_mla_dmaendB
	s_add_i32 s30, s55, 2
	s_cmp_ge_u32 s30, s20
	s_cselect_b64 s[60:61], -1, 0
	s_cbranch_scc1 .Latt_mla_dmaendB
	s_cmp_lt_u32 s55, 2
	s_cselect_b32 s62, s51, s49
	s_mul_i32 s57, s52, 0x6400
	s_add_i32 s57, s57, s42
	s_mov_b32 m0, s57
	v_mad_u32_u24 v217, s62, v237, v222
	global_load_lds_dwordx4 v217, s[2:3]
	s_add_i32 m0, s57, 0x2000
	v_mad_u32_u24 v217, s62, v239, v224
	global_load_lds_dwordx4 v217, s[2:3]
	s_add_i32 m0, s57, 0x4000
	v_mad_u32_u24 v217, s62, v241, v226
	global_load_lds_dwordx4 v217, s[2:3]
	s_ashr_i32 s63, s62, 31
	s_lshl_b64 s[30:31], s[62:63], 1
	s_mul_i32 s63, s52, 0x4800
	s_add_i32 s63, s63, s42
	s_add_i32 m0, s63, 0x12c00
	s_add_u32 s30, s21, s30
	s_addc_u32 s31, s43, s31
	global_load_lds_dwordx4 v202, s[30:31]
	s_add_i32 m0, s63, 0x14c00
	s_and_b64 vcc, exec, s[18:19]
	global_load_lds_dwordx4 v200, s[30:31]
	s_cbranch_vccz .Latt_mla_dmaxB
.Latt_mla_dmaendB:
	s_cmp_eq_u32 s55, 0
	s_cselect_b32 s31, 0xff7fffff, 0
	s_nop 4
	v_max3_f32 v215, v80, v81, v82
	v_max3_f32 v209, v83, v84, v85
	v_max3_f32 v215, v215, v86, v87
	v_max3_f32 v209, v209, v88, v89
	v_max3_f32 v215, v215, v90, v91
	v_max3_f32 v209, v209, v92, v93
	v_max3_f32 v215, v215, v94, v95
	v_max3_f32 v209, v209, v211, v213
	v_max_f32_e32 v209, v209, v215
	v_cmp_lt_f32_e32 vcc, s58, v209
	s_cmp_eq_u32 s55, 0
	s_cbranch_scc1 .Latt_mla_rare
	s_cbranch_vccnz .Latt_mla_rare
